# top-k rank count loop rewritten: per-candidate next-below thresholds turn (gt || (eq && idx<)) into one f32 compare + one add-with-carry, no scalar mask ops
# speedup vs baseline: 1.0059x; 1.0010x over previous
; #define LDS_FENCE() asm volatile("s_waitcnt lgkmcnt(0)" ::: "memory")
; DI void nsa_wg_unit(const Args& a, int l, int b, int g, int tb, unsigned char* lds, int tid_in, bool stage) {
;     ...
;       LDS_FENCE();
; #pragma unroll
;       for (int c = 0; c < CPL; ++c) IA[tok * 65 + qtr * CPL + c] = mv[c];
;       LDS_FENCE();
;       int cnt[CPL];
; #pragma unroll
;       for (int c = 0; c < CPL; ++c) cnt[c] = (qtr * CPL + c <= jt) ? 0 : 64;
;       if (jt >= 16)
; #pragma unroll 4
;       for (int i = 0; i < 64; ++i) { const float vi = IA[tok * 65 + i];
; #pragma unroll
;           for (int c = 0; c < CPL; ++c) { const int j = qtr * CPL + c; cnt[c] += ((vi > mv[c]) || (vi == mv[c] && i < j)) ? 1 : 0; } }
.LBB0_154:
	s_or_b64 exec, exec, s[0:1]
	v_cmp_lt_u32_e32 vcc, s33, v0
	v_mul_u32_u24_e32 v30, 0x104, v1
	v_lshlrev_b32_e32 v1, 5, v32
	v_cndmask_b32_e64 v34, 0, 64, vcc
	v_cmp_gt_u32_e32 vcc, s33, v0
	v_add3_u32 v1, s9, v30, v1
	s_waitcnt lgkmcnt(0)
	ds_write2_b32 v1, v4, v2 offset1:1
	ds_write2_b32 v1, v10, v8 offset0:2 offset1:3
	ds_write2_b32 v1, v18, v16 offset0:4 offset1:5
	ds_write2_b32 v1, v26, v24 offset0:6 offset1:7
	v_cndmask_b32_e64 v37, 64, 0, vcc
	v_cmp_lt_u32_e32 vcc, s33, v6
	s_waitcnt lgkmcnt(0)
	s_cmp_lt_u32 s33, 16
	s_nop 0
	v_cndmask_b32_e64 v40, 0, 64, vcc
	v_cmp_lt_u32_e32 vcc, s33, v12
	s_nop 1
	v_cndmask_b32_e64 v45, 0, 64, vcc
	v_cmp_lt_u32_e32 vcc, s33, v14
	s_nop 1
	v_cndmask_b32_e64 v46, 0, 64, vcc
	v_cmp_lt_u32_e32 vcc, s33, v20
	s_nop 1
	v_cndmask_b32_e64 v42, 0, 64, vcc
	v_cmp_lt_u32_e32 vcc, s33, v22
	s_nop 1
	v_cndmask_b32_e64 v38, 0, 64, vcc
	v_cmp_lt_u32_e32 vcc, s33, v28
	s_nop 1
	v_cndmask_b32_e64 v35, 0, 64, vcc
	s_cbranch_scc1 .LBB0_158
	v_mov_b32_e32 v1, v4
	v_mov_b32_e32 v3, v0
	v_mov_b32_e32 v5, v2
	v_mov_b32_e32 v7, v10
	v_mov_b32_e32 v9, v6
	v_mov_b32_e32 v11, v8
	v_mov_b32_e32 v13, v12
	v_mov_b32_e32 v15, v18
	v_mov_b32_e32 v17, v14
	v_mov_b32_e32 v19, v16
	v_mov_b32_e32 v21, v20
	v_mov_b32_e32 v23, v26
	v_mov_b32_e32 v25, v22
	v_mov_b32_e32 v27, v24
	v_mov_b32_e32 v29, v28
	v_add_u32_e32 v33, s8, v30
	s_mov_b32 s0, 1
	s_mov_b32 s1, 0
	v_mov_b32_e32 v36, 0
	v_mov_b32_e32 v39, 0
	v_mov_b32_e32 v43, 0
	v_mov_b32_e32 v47, 0
	v_mov_b32_e32 v49, 0
	v_mov_b32_e32 v48, 0
	v_mov_b32_e32 v44, 0
	v_mov_b32_e32 v41, 0
	s_mov_b32 s19, 0
	v_add_u32_e32 v33, 0x19e00, v33
	v_mov_b32_e32 v68, 0x80000001
	v_ashrrev_i32_e32 v31, 31, v4
	v_or_b32_e32 v31, 1, v31
	v_sub_u32_e32 v1, v4, v31
	v_cmp_eq_u32_e32 vcc, 0, v4
	s_nop 1
	v_cndmask_b32_e32 v1, v1, v68, vcc
	v_ashrrev_i32_e32 v31, 31, v2
	v_or_b32_e32 v31, 1, v31
	v_sub_u32_e32 v3, v2, v31
	v_cmp_eq_u32_e32 vcc, 0, v2
	s_nop 1
	v_cndmask_b32_e32 v3, v3, v68, vcc
	v_ashrrev_i32_e32 v31, 31, v10
	v_or_b32_e32 v31, 1, v31
	v_sub_u32_e32 v5, v10, v31
	v_cmp_eq_u32_e32 vcc, 0, v10
	s_nop 1
	v_cndmask_b32_e32 v5, v5, v68, vcc
	v_ashrrev_i32_e32 v31, 31, v8
	v_or_b32_e32 v31, 1, v31
	v_sub_u32_e32 v7, v8, v31
	v_cmp_eq_u32_e32 vcc, 0, v8
	s_nop 1
	v_cndmask_b32_e32 v7, v7, v68, vcc
	v_ashrrev_i32_e32 v31, 31, v18
	v_or_b32_e32 v31, 1, v31
	v_sub_u32_e32 v9, v18, v31
	v_cmp_eq_u32_e32 vcc, 0, v18
	s_nop 1
	v_cndmask_b32_e32 v9, v9, v68, vcc
	v_ashrrev_i32_e32 v31, 31, v16
	v_or_b32_e32 v31, 1, v31
	v_sub_u32_e32 v11, v16, v31
	v_cmp_eq_u32_e32 vcc, 0, v16
	s_nop 1
	v_cndmask_b32_e32 v11, v11, v68, vcc
	v_ashrrev_i32_e32 v31, 31, v26
	v_or_b32_e32 v31, 1, v31
	v_sub_u32_e32 v13, v26, v31
	v_cmp_eq_u32_e32 vcc, 0, v26
	s_nop 1
	v_cndmask_b32_e32 v13, v13, v68, vcc
	v_ashrrev_i32_e32 v31, 31, v24
	v_or_b32_e32 v31, 1, v31
	v_sub_u32_e32 v15, v24, v31
	v_cmp_eq_u32_e32 vcc, 0, v24
	s_nop 1
	v_cndmask_b32_e32 v15, v15, v68, vcc
	s_add_i32 s98, s33, 8
	s_lshr_b32 s98, s98, 3
	s_mov_b32 s99, 0
; DI void nsa_wg_unit(const Args& a, int l, int b, int g, int tb, unsigned char* lds, int tid_in, bool stage) {
;     ...
;       for (int i = 0; i < 64; ++i) { const float vi = IA[tok * 65 + i];
; #pragma unroll
;           for (int c = 0; c < CPL; ++c) { const int j = qtr * CPL + c; cnt[c] += ((vi > mv[c]) || (vi == mv[c] && i < j)) ? 1 : 0; } }
.LBB0_156:
	v_cmp_le_u32_e64 s[6:7], s99, v32
	v_cmp_lt_u32_e64 s[8:9], s99, v32
	ds_read2_b32 v[58:59], v33 offset1:1
	ds_read2_b32 v[62:63], v33 offset0:2 offset1:3
	ds_read2_b32 v[66:67], v33 offset0:4 offset1:5
	ds_read_b32 v61, v33 offset:24
	ds_read_b32 v64, v33 offset:28
	v_cndmask_b32_e64 v17, v4, v1, s[6:7]
	v_cndmask_b32_e64 v19, v2, v3, s[6:7]
	v_cndmask_b32_e64 v21, v10, v5, s[6:7]
	v_cndmask_b32_e64 v23, v8, v7, s[6:7]
	v_cndmask_b32_e64 v25, v18, v9, s[6:7]
	v_cndmask_b32_e64 v27, v16, v11, s[6:7]
	v_cndmask_b32_e64 v29, v26, v13, s[6:7]
	v_cndmask_b32_e64 v30, v24, v15, s[6:7]
	v_cndmask_b32_e64 v50, v4, v1, s[8:9]
	v_cndmask_b32_e64 v51, v2, v3, s[8:9]
	v_cndmask_b32_e64 v52, v10, v5, s[8:9]
	v_cndmask_b32_e64 v53, v8, v7, s[8:9]
	v_cndmask_b32_e64 v54, v18, v9, s[8:9]
	v_cndmask_b32_e64 v55, v16, v11, s[8:9]
	v_cndmask_b32_e64 v56, v26, v13, s[8:9]
	v_cndmask_b32_e64 v57, v24, v15, s[8:9]
	s_waitcnt lgkmcnt(0)
	v_cmp_gt_f32_e64 s[8:9], v58, v50
	v_cmp_gt_f32_e64 s[10:11], v58, v19
	v_cmp_gt_f32_e64 s[12:13], v58, v21
	v_addc_co_u32_e64 v41, vcc, 0, v41, s[8:9]
	v_cmp_gt_f32_e64 s[14:15], v58, v23
	v_addc_co_u32_e64 v44, vcc, 0, v44, s[10:11]
	v_cmp_gt_f32_e64 s[8:9], v58, v25
	v_addc_co_u32_e64 v48, vcc, 0, v48, s[12:13]
	v_cmp_gt_f32_e64 s[10:11], v58, v27
	v_addc_co_u32_e64 v49, vcc, 0, v49, s[14:15]
	v_cmp_gt_f32_e64 s[12:13], v58, v29
	v_addc_co_u32_e64 v47, vcc, 0, v47, s[8:9]
	v_cmp_gt_f32_e64 s[14:15], v58, v30
	v_addc_co_u32_e64 v43, vcc, 0, v43, s[10:11]
	v_cmp_gt_f32_e64 s[8:9], v59, v50
	v_addc_co_u32_e64 v39, vcc, 0, v39, s[12:13]
	v_cmp_gt_f32_e64 s[10:11], v59, v51
	v_addc_co_u32_e64 v36, vcc, 0, v36, s[14:15]
	v_cmp_gt_f32_e64 s[12:13], v59, v21
	v_addc_co_u32_e64 v41, vcc, 0, v41, s[8:9]
	v_cmp_gt_f32_e64 s[14:15], v59, v23
	v_addc_co_u32_e64 v44, vcc, 0, v44, s[10:11]
	v_cmp_gt_f32_e64 s[8:9], v59, v25
	v_addc_co_u32_e64 v48, vcc, 0, v48, s[12:13]
	v_cmp_gt_f32_e64 s[10:11], v59, v27
	v_addc_co_u32_e64 v49, vcc, 0, v49, s[14:15]
	v_cmp_gt_f32_e64 s[12:13], v59, v29
	v_addc_co_u32_e64 v47, vcc, 0, v47, s[8:9]
	v_cmp_gt_f32_e64 s[14:15], v59, v30
	v_addc_co_u32_e64 v43, vcc, 0, v43, s[10:11]
	v_cmp_gt_f32_e64 s[8:9], v62, v50
	v_addc_co_u32_e64 v39, vcc, 0, v39, s[12:13]
	v_cmp_gt_f32_e64 s[10:11], v62, v51
	v_addc_co_u32_e64 v36, vcc, 0, v36, s[14:15]
	v_cmp_gt_f32_e64 s[12:13], v62, v52
	v_addc_co_u32_e64 v41, vcc, 0, v41, s[8:9]
	v_cmp_gt_f32_e64 s[14:15], v62, v23
	v_addc_co_u32_e64 v44, vcc, 0, v44, s[10:11]
	v_cmp_gt_f32_e64 s[8:9], v62, v25
	v_addc_co_u32_e64 v48, vcc, 0, v48, s[12:13]
	v_cmp_gt_f32_e64 s[10:11], v62, v27
	v_addc_co_u32_e64 v49, vcc, 0, v49, s[14:15]
	v_cmp_gt_f32_e64 s[12:13], v62, v29
	v_addc_co_u32_e64 v47, vcc, 0, v47, s[8:9]
	v_cmp_gt_f32_e64 s[14:15], v62, v30
	v_addc_co_u32_e64 v43, vcc, 0, v43, s[10:11]
	v_cmp_gt_f32_e64 s[8:9], v63, v50
	v_addc_co_u32_e64 v39, vcc, 0, v39, s[12:13]
	v_cmp_gt_f32_e64 s[10:11], v63, v51
	v_addc_co_u32_e64 v36, vcc, 0, v36, s[14:15]
	v_cmp_gt_f32_e64 s[12:13], v63, v52
	v_addc_co_u32_e64 v41, vcc, 0, v41, s[8:9]
	v_cmp_gt_f32_e64 s[14:15], v63, v53
	v_addc_co_u32_e64 v44, vcc, 0, v44, s[10:11]
	v_cmp_gt_f32_e64 s[8:9], v63, v25
	v_addc_co_u32_e64 v48, vcc, 0, v48, s[12:13]
	v_cmp_gt_f32_e64 s[10:11], v63, v27
	v_addc_co_u32_e64 v49, vcc, 0, v49, s[14:15]
	v_cmp_gt_f32_e64 s[12:13], v63, v29
	v_addc_co_u32_e64 v47, vcc, 0, v47, s[8:9]
	v_cmp_gt_f32_e64 s[14:15], v63, v30
	v_addc_co_u32_e64 v43, vcc, 0, v43, s[10:11]
	v_cmp_gt_f32_e64 s[8:9], v66, v50
	v_addc_co_u32_e64 v39, vcc, 0, v39, s[12:13]
	v_cmp_gt_f32_e64 s[10:11], v66, v51
	v_addc_co_u32_e64 v36, vcc, 0, v36, s[14:15]
	v_cmp_gt_f32_e64 s[12:13], v66, v52
	v_addc_co_u32_e64 v41, vcc, 0, v41, s[8:9]
	v_cmp_gt_f32_e64 s[14:15], v66, v53
	v_addc_co_u32_e64 v44, vcc, 0, v44, s[10:11]
	v_cmp_gt_f32_e64 s[8:9], v66, v54
	v_addc_co_u32_e64 v48, vcc, 0, v48, s[12:13]
	v_cmp_gt_f32_e64 s[10:11], v66, v27
	v_addc_co_u32_e64 v49, vcc, 0, v49, s[14:15]
	v_cmp_gt_f32_e64 s[12:13], v66, v29
	v_addc_co_u32_e64 v47, vcc, 0, v47, s[8:9]
	v_cmp_gt_f32_e64 s[14:15], v66, v30
	v_addc_co_u32_e64 v43, vcc, 0, v43, s[10:11]
	v_cmp_gt_f32_e64 s[8:9], v67, v50
	v_addc_co_u32_e64 v39, vcc, 0, v39, s[12:13]
	v_cmp_gt_f32_e64 s[10:11], v67, v51
	v_addc_co_u32_e64 v36, vcc, 0, v36, s[14:15]
	v_cmp_gt_f32_e64 s[12:13], v67, v52
	v_addc_co_u32_e64 v41, vcc, 0, v41, s[8:9]
	v_cmp_gt_f32_e64 s[14:15], v67, v53
	v_addc_co_u32_e64 v44, vcc, 0, v44, s[10:11]
	v_cmp_gt_f32_e64 s[8:9], v67, v54
	v_addc_co_u32_e64 v48, vcc, 0, v48, s[12:13]
	v_cmp_gt_f32_e64 s[10:11], v67, v55
	v_addc_co_u32_e64 v49, vcc, 0, v49, s[14:15]
	v_cmp_gt_f32_e64 s[12:13], v67, v29
	v_addc_co_u32_e64 v47, vcc, 0, v47, s[8:9]
	v_cmp_gt_f32_e64 s[14:15], v67, v30
	v_addc_co_u32_e64 v43, vcc, 0, v43, s[10:11]
	v_cmp_gt_f32_e64 s[8:9], v61, v50
	v_addc_co_u32_e64 v39, vcc, 0, v39, s[12:13]
	v_cmp_gt_f32_e64 s[10:11], v61, v51
	v_addc_co_u32_e64 v36, vcc, 0, v36, s[14:15]
	v_cmp_gt_f32_e64 s[12:13], v61, v52
	v_addc_co_u32_e64 v41, vcc, 0, v41, s[8:9]
	v_cmp_gt_f32_e64 s[14:15], v61, v53
	v_addc_co_u32_e64 v44, vcc, 0, v44, s[10:11]
	v_cmp_gt_f32_e64 s[8:9], v61, v54
	v_addc_co_u32_e64 v48, vcc, 0, v48, s[12:13]
	v_cmp_gt_f32_e64 s[10:11], v61, v55
	v_addc_co_u32_e64 v49, vcc, 0, v49, s[14:15]
	v_cmp_gt_f32_e64 s[12:13], v61, v56
	v_addc_co_u32_e64 v47, vcc, 0, v47, s[8:9]
	v_cmp_gt_f32_e64 s[14:15], v61, v30
	v_addc_co_u32_e64 v43, vcc, 0, v43, s[10:11]
	v_cmp_gt_f32_e64 s[8:9], v64, v50
	v_addc_co_u32_e64 v39, vcc, 0, v39, s[12:13]
	v_cmp_gt_f32_e64 s[10:11], v64, v51
	v_addc_co_u32_e64 v36, vcc, 0, v36, s[14:15]
	v_cmp_gt_f32_e64 s[12:13], v64, v52
	v_addc_co_u32_e64 v41, vcc, 0, v41, s[8:9]
	v_cmp_gt_f32_e64 s[14:15], v64, v53
	v_addc_co_u32_e64 v44, vcc, 0, v44, s[10:11]
	v_cmp_gt_f32_e64 s[8:9], v64, v54
	v_addc_co_u32_e64 v48, vcc, 0, v48, s[12:13]
	v_cmp_gt_f32_e64 s[10:11], v64, v55
	v_addc_co_u32_e64 v49, vcc, 0, v49, s[14:15]
	v_cmp_gt_f32_e64 s[12:13], v64, v56
	v_addc_co_u32_e64 v47, vcc, 0, v47, s[8:9]
	v_cmp_gt_f32_e64 s[14:15], v64, v57
	v_addc_co_u32_e64 v43, vcc, 0, v43, s[10:11]
	v_addc_co_u32_e64 v39, vcc, 0, v39, s[12:13]
	v_addc_co_u32_e64 v36, vcc, 0, v36, s[14:15]
	v_add_u32_e32 v33, 32, v33
	s_add_i32 s99, s99, 1
	s_cmp_lt_u32 s99, s98
	s_cbranch_scc1 .LBB0_156
	v_add_u32_e32 v34, v34, v41
	v_add_u32_e32 v37, v37, v44
	v_add_u32_e32 v40, v40, v48
	v_add_u32_e32 v45, v45, v49
	v_add_u32_e32 v46, v46, v47
	v_add_u32_e32 v42, v42, v43
	v_add_u32_e32 v38, v38, v39
	v_add_u32_e32 v35, v35, v36

; #define LDS_FENCE() asm volatile("s_waitcnt lgkmcnt(0)" ::: "memory")
; DI void nsa_wg_unit(const Args& a, int l, int b, int g, int tb, unsigned char* lds, int tid_in, bool stage) {
;     ...
;       LDS_FENCE();
; #pragma unroll
;       for (int c = 0; c < CPL; ++c) IA[tok * 65 + qtr * CPL + c] = mv[c];
;       LDS_FENCE();
;       int cnt[CPL];
; #pragma unroll
;       for (int c = 0; c < CPL; ++c) cnt[c] = (qtr * CPL + c <= jt) ? 0 : 64;
;       if (jt >= 16)
; #pragma unroll 4
;       for (int i = 0; i < 64; ++i) { const float vi = IA[tok * 65 + i];
; #pragma unroll
;           for (int c = 0; c < CPL; ++c) { const int j = qtr * CPL + c; cnt[c] += ((vi > mv[c]) || (vi == mv[c] && i < j)) ? 1 : 0; } }
.LBB0_233:
	s_or_b64 exec, exec, s[0:1]
	v_cmp_lt_u32_e32 vcc, s93, v28
	v_mul_u32_u24_e32 v1, 0x104, v30
	v_lshlrev_b32_e32 v3, 5, v32
	v_cndmask_b32_e64 v34, 0, 64, vcc
	v_cmp_lt_u32_e32 vcc, s93, v22
	v_add3_u32 v1, s9, v1, v3
	s_waitcnt lgkmcnt(0)
	ds_write2_b32 v1, v4, v2 offset1:1
	ds_write2_b32 v1, v10, v8 offset0:2 offset1:3
	ds_write2_b32 v1, v18, v16 offset0:4 offset1:5
	ds_write2_b32 v1, v26, v24 offset0:6 offset1:7
	v_cndmask_b32_e64 v37, 0, 64, vcc
	v_cmp_lt_u32_e32 vcc, s93, v20
	s_waitcnt lgkmcnt(0)
	v_mov_b32_e32 v31, s8
	s_movk_i32 s1, 0x104
	v_cndmask_b32_e64 v41, 0, 64, vcc
	v_cmp_lt_u32_e32 vcc, s93, v14
	s_mov_b32 s0, 0
	v_mov_b32_e32 v1, v24
	v_cndmask_b32_e64 v45, 0, 64, vcc
	v_cmp_lt_u32_e32 vcc, s93, v12
	v_mov_b32_e32 v3, v4
	v_mov_b32_e32 v5, v0
	v_cndmask_b32_e64 v48, 0, 64, vcc
	v_cmp_lt_u32_e32 vcc, s93, v6
	v_mov_b32_e32 v7, v2
	v_mov_b32_e32 v9, v10
	v_cndmask_b32_e64 v44, 0, 64, vcc
	v_cmp_gt_u32_e32 vcc, s93, v0
	v_mov_b32_e32 v11, v6
	v_mov_b32_e32 v13, v8
	v_cndmask_b32_e64 v40, 64, 0, vcc
	v_cmp_lt_u32_e32 vcc, s93, v0
	v_mov_b32_e32 v15, v12
	v_mov_b32_e32 v17, v18
	v_cndmask_b32_e64 v36, 0, 64, vcc
	v_mov_b32_e32 v19, v14
	v_mov_b32_e32 v21, v16
	v_mov_b32_e32 v23, v20
	v_mov_b32_e32 v25, v26
	v_mov_b32_e32 v27, v22
	v_mov_b32_e32 v29, v28
	v_mad_u32_u24 v33, v30, s1, v31
	s_mov_b32 s1, 1
	v_mov_b32_e32 v35, 0
	v_mov_b32_e32 v38, 0
	v_mov_b32_e32 v42, 0
	v_mov_b32_e32 v46, 0
	v_mov_b32_e32 v49, 0
	v_mov_b32_e32 v47, 0
	v_mov_b32_e32 v43, 0
	v_mov_b32_e32 v39, 0
	s_mov_b32 s17, 0
	v_add_u32_e32 v33, 0x19e00, v33
	v_mov_b32_e32 v68, 0x80000001
	v_ashrrev_i32_e32 v31, 31, v4
	v_or_b32_e32 v31, 1, v31
	v_sub_u32_e32 v1, v4, v31
	v_cmp_eq_u32_e32 vcc, 0, v4
	s_nop 1
	v_cndmask_b32_e32 v1, v1, v68, vcc
	v_ashrrev_i32_e32 v31, 31, v2
	v_or_b32_e32 v31, 1, v31
	v_sub_u32_e32 v3, v2, v31
	v_cmp_eq_u32_e32 vcc, 0, v2
	s_nop 1
	v_cndmask_b32_e32 v3, v3, v68, vcc
	v_ashrrev_i32_e32 v31, 31, v10
	v_or_b32_e32 v31, 1, v31
	v_sub_u32_e32 v5, v10, v31
	v_cmp_eq_u32_e32 vcc, 0, v10
	s_nop 1
	v_cndmask_b32_e32 v5, v5, v68, vcc
	v_ashrrev_i32_e32 v31, 31, v8
	v_or_b32_e32 v31, 1, v31
	v_sub_u32_e32 v7, v8, v31
	v_cmp_eq_u32_e32 vcc, 0, v8
	s_nop 1
	v_cndmask_b32_e32 v7, v7, v68, vcc
	v_ashrrev_i32_e32 v31, 31, v18
	v_or_b32_e32 v31, 1, v31
	v_sub_u32_e32 v9, v18, v31
	v_cmp_eq_u32_e32 vcc, 0, v18
	s_nop 1
	v_cndmask_b32_e32 v9, v9, v68, vcc
	v_ashrrev_i32_e32 v31, 31, v16
	v_or_b32_e32 v31, 1, v31
	v_sub_u32_e32 v11, v16, v31
	v_cmp_eq_u32_e32 vcc, 0, v16
	s_nop 1
	v_cndmask_b32_e32 v11, v11, v68, vcc
	v_ashrrev_i32_e32 v31, 31, v26
	v_or_b32_e32 v31, 1, v31
	v_sub_u32_e32 v13, v26, v31
	v_cmp_eq_u32_e32 vcc, 0, v26
	s_nop 1
	v_cndmask_b32_e32 v13, v13, v68, vcc
	v_ashrrev_i32_e32 v31, 31, v24
	v_or_b32_e32 v31, 1, v31
	v_sub_u32_e32 v15, v24, v31
	v_cmp_eq_u32_e32 vcc, 0, v24
	s_nop 1
	v_cndmask_b32_e32 v15, v15, v68, vcc
	s_add_i32 s98, s93, 8
	s_lshr_b32 s98, s98, 3
	s_mov_b32 s99, 0
.LBB0_234:
	v_cmp_le_u32_e64 s[6:7], s99, v32
	v_cmp_lt_u32_e64 s[8:9], s99, v32
	ds_read2_b32 v[58:59], v33 offset1:1
	ds_read2_b32 v[62:63], v33 offset0:2 offset1:3
	ds_read2_b32 v[66:67], v33 offset0:4 offset1:5
	ds_read_b32 v61, v33 offset:24
	ds_read_b32 v64, v33 offset:28
	v_cndmask_b32_e64 v17, v4, v1, s[6:7]
	v_cndmask_b32_e64 v19, v2, v3, s[6:7]
	v_cndmask_b32_e64 v21, v10, v5, s[6:7]
	v_cndmask_b32_e64 v23, v8, v7, s[6:7]
	v_cndmask_b32_e64 v25, v18, v9, s[6:7]
	v_cndmask_b32_e64 v27, v16, v11, s[6:7]
	v_cndmask_b32_e64 v29, v26, v13, s[6:7]
	v_cndmask_b32_e64 v30, v24, v15, s[6:7]
	v_cndmask_b32_e64 v50, v4, v1, s[8:9]
	v_cndmask_b32_e64 v51, v2, v3, s[8:9]
	v_cndmask_b32_e64 v52, v10, v5, s[8:9]
	v_cndmask_b32_e64 v53, v8, v7, s[8:9]
	v_cndmask_b32_e64 v54, v18, v9, s[8:9]
	v_cndmask_b32_e64 v55, v16, v11, s[8:9]
	v_cndmask_b32_e64 v56, v26, v13, s[8:9]
	v_cndmask_b32_e64 v57, v24, v15, s[8:9]
	s_waitcnt lgkmcnt(0)
	v_cmp_gt_f32_e64 s[8:9], v58, v50
	v_cmp_gt_f32_e64 s[10:11], v58, v19
	v_cmp_gt_f32_e64 s[12:13], v58, v21
	v_addc_co_u32_e64 v39, vcc, 0, v39, s[8:9]
	v_cmp_gt_f32_e64 s[14:15], v58, v23
	v_addc_co_u32_e64 v43, vcc, 0, v43, s[10:11]
	v_cmp_gt_f32_e64 s[8:9], v58, v25
	v_addc_co_u32_e64 v47, vcc, 0, v47, s[12:13]
	v_cmp_gt_f32_e64 s[10:11], v58, v27
	v_addc_co_u32_e64 v49, vcc, 0, v49, s[14:15]
	v_cmp_gt_f32_e64 s[12:13], v58, v29
	v_addc_co_u32_e64 v46, vcc, 0, v46, s[8:9]
	v_cmp_gt_f32_e64 s[14:15], v58, v30
	v_addc_co_u32_e64 v42, vcc, 0, v42, s[10:11]
	v_cmp_gt_f32_e64 s[8:9], v59, v50
	v_addc_co_u32_e64 v38, vcc, 0, v38, s[12:13]
	v_cmp_gt_f32_e64 s[10:11], v59, v51
	v_addc_co_u32_e64 v35, vcc, 0, v35, s[14:15]
	v_cmp_gt_f32_e64 s[12:13], v59, v21
	v_addc_co_u32_e64 v39, vcc, 0, v39, s[8:9]
	v_cmp_gt_f32_e64 s[14:15], v59, v23
	v_addc_co_u32_e64 v43, vcc, 0, v43, s[10:11]
	v_cmp_gt_f32_e64 s[8:9], v59, v25
	v_addc_co_u32_e64 v47, vcc, 0, v47, s[12:13]
	v_cmp_gt_f32_e64 s[10:11], v59, v27
	v_addc_co_u32_e64 v49, vcc, 0, v49, s[14:15]
	v_cmp_gt_f32_e64 s[12:13], v59, v29
	v_addc_co_u32_e64 v46, vcc, 0, v46, s[8:9]
	v_cmp_gt_f32_e64 s[14:15], v59, v30
	v_addc_co_u32_e64 v42, vcc, 0, v42, s[10:11]
	v_cmp_gt_f32_e64 s[8:9], v62, v50
	v_addc_co_u32_e64 v38, vcc, 0, v38, s[12:13]
	v_cmp_gt_f32_e64 s[10:11], v62, v51
	v_addc_co_u32_e64 v35, vcc, 0, v35, s[14:15]
	v_cmp_gt_f32_e64 s[12:13], v62, v52
	v_addc_co_u32_e64 v39, vcc, 0, v39, s[8:9]
	v_cmp_gt_f32_e64 s[14:15], v62, v23
	v_addc_co_u32_e64 v43, vcc, 0, v43, s[10:11]
	v_cmp_gt_f32_e64 s[8:9], v62, v25
	v_addc_co_u32_e64 v47, vcc, 0, v47, s[12:13]
	v_cmp_gt_f32_e64 s[10:11], v62, v27
	v_addc_co_u32_e64 v49, vcc, 0, v49, s[14:15]
	v_cmp_gt_f32_e64 s[12:13], v62, v29
; DI void nsa_wg_unit(const Args& a, int l, int b, int g, int tb, unsigned char* lds, int tid_in, bool stage) {
;     ...
;       for (int i = 0; i < 64; ++i) { const float vi = IA[tok * 65 + i];
; #pragma unroll
;           for (int c = 0; c < CPL; ++c) { const int j = qtr * CPL + c; cnt[c] += ((vi > mv[c]) || (vi == mv[c] && i < j)) ? 1 : 0; } }
	v_addc_co_u32_e64 v46, vcc, 0, v46, s[8:9]
	v_cmp_gt_f32_e64 s[14:15], v62, v30
	v_addc_co_u32_e64 v42, vcc, 0, v42, s[10:11]
	v_cmp_gt_f32_e64 s[8:9], v63, v50
	v_addc_co_u32_e64 v38, vcc, 0, v38, s[12:13]
	v_cmp_gt_f32_e64 s[10:11], v63, v51
	v_addc_co_u32_e64 v35, vcc, 0, v35, s[14:15]
	v_cmp_gt_f32_e64 s[12:13], v63, v52
	v_addc_co_u32_e64 v39, vcc, 0, v39, s[8:9]
	v_cmp_gt_f32_e64 s[14:15], v63, v53
	v_addc_co_u32_e64 v43, vcc, 0, v43, s[10:11]
	v_cmp_gt_f32_e64 s[8:9], v63, v25
	v_addc_co_u32_e64 v47, vcc, 0, v47, s[12:13]
	v_cmp_gt_f32_e64 s[10:11], v63, v27
	v_addc_co_u32_e64 v49, vcc, 0, v49, s[14:15]
	v_cmp_gt_f32_e64 s[12:13], v63, v29
	v_addc_co_u32_e64 v46, vcc, 0, v46, s[8:9]
	v_cmp_gt_f32_e64 s[14:15], v63, v30
	v_addc_co_u32_e64 v42, vcc, 0, v42, s[10:11]
	v_cmp_gt_f32_e64 s[8:9], v66, v50
	v_addc_co_u32_e64 v38, vcc, 0, v38, s[12:13]
	v_cmp_gt_f32_e64 s[10:11], v66, v51
	v_addc_co_u32_e64 v35, vcc, 0, v35, s[14:15]
	v_cmp_gt_f32_e64 s[12:13], v66, v52
	v_addc_co_u32_e64 v39, vcc, 0, v39, s[8:9]
	v_cmp_gt_f32_e64 s[14:15], v66, v53
	v_addc_co_u32_e64 v43, vcc, 0, v43, s[10:11]
	v_cmp_gt_f32_e64 s[8:9], v66, v54
	v_addc_co_u32_e64 v47, vcc, 0, v47, s[12:13]
	v_cmp_gt_f32_e64 s[10:11], v66, v27
	v_addc_co_u32_e64 v49, vcc, 0, v49, s[14:15]
	v_cmp_gt_f32_e64 s[12:13], v66, v29
	v_addc_co_u32_e64 v46, vcc, 0, v46, s[8:9]
	v_cmp_gt_f32_e64 s[14:15], v66, v30
	v_addc_co_u32_e64 v42, vcc, 0, v42, s[10:11]
	v_cmp_gt_f32_e64 s[8:9], v67, v50
	v_addc_co_u32_e64 v38, vcc, 0, v38, s[12:13]
	v_cmp_gt_f32_e64 s[10:11], v67, v51
	v_addc_co_u32_e64 v35, vcc, 0, v35, s[14:15]
	v_cmp_gt_f32_e64 s[12:13], v67, v52
	v_addc_co_u32_e64 v39, vcc, 0, v39, s[8:9]
	v_cmp_gt_f32_e64 s[14:15], v67, v53
	v_addc_co_u32_e64 v43, vcc, 0, v43, s[10:11]
	v_cmp_gt_f32_e64 s[8:9], v67, v54
	v_addc_co_u32_e64 v47, vcc, 0, v47, s[12:13]
	v_cmp_gt_f32_e64 s[10:11], v67, v55
	v_addc_co_u32_e64 v49, vcc, 0, v49, s[14:15]
	v_cmp_gt_f32_e64 s[12:13], v67, v29
	v_addc_co_u32_e64 v46, vcc, 0, v46, s[8:9]
	v_cmp_gt_f32_e64 s[14:15], v67, v30
	v_addc_co_u32_e64 v42, vcc, 0, v42, s[10:11]
	v_cmp_gt_f32_e64 s[8:9], v61, v50
	v_addc_co_u32_e64 v38, vcc, 0, v38, s[12:13]
	v_cmp_gt_f32_e64 s[10:11], v61, v51
	v_addc_co_u32_e64 v35, vcc, 0, v35, s[14:15]
	v_cmp_gt_f32_e64 s[12:13], v61, v52
	v_addc_co_u32_e64 v39, vcc, 0, v39, s[8:9]
	v_cmp_gt_f32_e64 s[14:15], v61, v53
	v_addc_co_u32_e64 v43, vcc, 0, v43, s[10:11]
	v_cmp_gt_f32_e64 s[8:9], v61, v54
	v_addc_co_u32_e64 v47, vcc, 0, v47, s[12:13]
	v_cmp_gt_f32_e64 s[10:11], v61, v55
	v_addc_co_u32_e64 v49, vcc, 0, v49, s[14:15]
	v_cmp_gt_f32_e64 s[12:13], v61, v56
	v_addc_co_u32_e64 v46, vcc, 0, v46, s[8:9]
	v_cmp_gt_f32_e64 s[14:15], v61, v30
	v_addc_co_u32_e64 v42, vcc, 0, v42, s[10:11]
	v_cmp_gt_f32_e64 s[8:9], v64, v50
	v_addc_co_u32_e64 v38, vcc, 0, v38, s[12:13]
	v_cmp_gt_f32_e64 s[10:11], v64, v51
	v_addc_co_u32_e64 v35, vcc, 0, v35, s[14:15]
	v_cmp_gt_f32_e64 s[12:13], v64, v52
	v_addc_co_u32_e64 v39, vcc, 0, v39, s[8:9]
	v_cmp_gt_f32_e64 s[14:15], v64, v53
	v_addc_co_u32_e64 v43, vcc, 0, v43, s[10:11]
	v_cmp_gt_f32_e64 s[8:9], v64, v54
	v_addc_co_u32_e64 v47, vcc, 0, v47, s[12:13]
	v_cmp_gt_f32_e64 s[10:11], v64, v55
	v_addc_co_u32_e64 v49, vcc, 0, v49, s[14:15]
	v_cmp_gt_f32_e64 s[12:13], v64, v56
	v_addc_co_u32_e64 v46, vcc, 0, v46, s[8:9]
	v_cmp_gt_f32_e64 s[14:15], v64, v57
	v_addc_co_u32_e64 v42, vcc, 0, v42, s[10:11]
	v_addc_co_u32_e64 v38, vcc, 0, v38, s[12:13]
	v_addc_co_u32_e64 v35, vcc, 0, v35, s[14:15]
	v_add_u32_e32 v33, 32, v33
	s_add_i32 s99, s99, 1
	s_cmp_lt_u32 s99, s98
	s_cbranch_scc1 .LBB0_234
; DI void nsa_wg_unit(const Args& a, int l, int b, int g, int tb, unsigned char* lds, int tid_in, bool stage) {
;     ...
;       unsigned mc = 0;
; #pragma unroll
;       for (int c = 0; c < CPL; ++c) mc |= (cnt[c] < 16) ? (1u << c) : 0u;
;       unsigned lo = 0, hi = 0;
; #pragma unroll
;       for (int k = 0; k < LPT / 2; ++k) { lo |= (unsigned)__shfl((int)mc, tok * LPT + k) << (CPL * k); hi |= (unsigned)__shfl((int)mc, tok * LPT + LPT / 2 + k) << (CPL * k); }
;       { const int src = (rl >> 2) * LPT; sel_lo[0] = (unsigned)__shfl((int)lo, src); sel_hi[0] = (unsigned)__shfl((int)hi, src); }
;       unsigned ul = lo, uh = hi;
; #pragma unroll
;       for (int o = LPT; o < 64; o <<= 1) { ul |= (unsigned)__shfl_xor((int)ul, o); uh |= (unsigned)__shfl_xor((int)uh, o); }
;       ulo = (unsigned)__builtin_amdgcn_readfirstlane((int)ul); uhi = (unsigned)__builtin_amdgcn_readfirstlane((int)uh); }
;     const unsigned long long myu = ((unsigned long long)uhi << 32) | (unsigned long long)ulo;
;     unsigned long long* UW = (unsigned long long*)(lds + AL_UW);
;     if (lane == 0) UW[wave] = myu;
;     __syncthreads();
;     unsigned long long wgu = 0ull;
; #pragma unroll
;     for (int w = 0; w < 8; ++w) wgu |= UW[w];
;     wgu = ((unsigned long long)(unsigned)__builtin_amdgcn_readfirstlane((int)(wgu >> 32)) << 32) | (unsigned long long)(unsigned)__builtin_amdgcn_readfirstlane((int)(unsigned)wgu);
;     const int srow = tid >> 3, sch = tid & 7;
;     const LP kfl = L + AL_KR + rl * KR_PB + 16 * h, vfl = L + AL_VR + rl * VR_PB + 8 * h;
;     attn_reset(st);
;     { unsigned long long rem = wgu & ((jt >= 63) ? ~0ull : ((1ull << (jt + 1)) - 1ull));
;       const unsigned koff = (unsigned)(srow * ZP + sch * 8) * 2u, voff = (unsigned)(srow * SEQ + sch * 8) * 2u;
;       const char* kgb = (const char*)(zb + C_KV + 2 * 128 + g * 64); const char* vgb = (const char*)VST;
;       int j = rem ? (int)__builtin_ctzll(rem) : -1, bi = 0; u32x4 kreg, vreg;
;       if (j >= 0) { kreg = *(const u32x4*)(kgb + (size_t)(64 * j) * ZP * 2 + koff); vreg = *(const u32x4*)(vgb + (size_t)(64 * j) * 2 + voff);
;           *(u32x4*)(lds + AL_KR + srow * KR_PB + sch * 16) = kreg; u32x2* d = (u32x2*)(lds + AL_VR + srow * VR_PB + sch * 16); u32x2 lo2, hi2; lo2.x = vreg.x; lo2.y = vreg.y; hi2.x = vreg.z; hi2.y = vreg.w; d[0] = lo2; d[1] = hi2; }
;       __syncthreads();
	v_add_u32_e32 v0, v36, v39
	v_add_u32_e32 v1, v40, v43
	v_cmp_gt_i32_e32 vcc, 16, v0
	v_add_u32_e32 v2, v44, v47
	v_add_u32_e32 v3, v48, v49
	v_cndmask_b32_e64 v0, 0, 1, vcc
	v_cmp_gt_i32_e32 vcc, 16, v1
	v_add_u32_e32 v4, v45, v46
	v_add_u32_e32 v5, v41, v42
	v_cndmask_b32_e64 v1, 0, 2, vcc
	v_cmp_gt_i32_e32 vcc, 16, v2
	v_or_b32_e32 v0, v1, v0
	v_add_u32_e32 v6, v37, v38
	v_cndmask_b32_e64 v1, 0, 4, vcc
	v_cmp_gt_i32_e32 vcc, 16, v3
	v_add_u32_e32 v7, v34, v35
	s_nop 0
	v_cndmask_b32_e64 v2, 0, 8, vcc
	v_cmp_gt_i32_e32 vcc, 16, v4
	v_or3_b32 v0, v0, v1, v2
	s_nop 0
	v_cndmask_b32_e64 v1, 0, 16, vcc
	v_cmp_gt_i32_e32 vcc, 16, v5
	s_nop 1
	v_cndmask_b32_e64 v2, 0, 32, vcc
	v_cmp_gt_i32_e32 vcc, 16, v6
	v_or3_b32 v0, v0, v1, v2
	s_nop 0
	v_cndmask_b32_e64 v1, 0, 64, vcc
	v_cmp_gt_i32_e32 vcc, 16, v7
	s_nop 1
	v_cndmask_b32_e32 v2, 0, v198, vcc
	v_or3_b32 v0, v0, v1, v2
	v_and_or_b32 v1, v74, 56, v149
	v_lshlrev_b32_e32 v1, 2, v1
	ds_bpermute_b32 v2, v1, v0
	ds_bpermute_b32 v3, v1, v0 offset:4
	ds_bpermute_b32 v4, v1, v0 offset:16
	ds_bpermute_b32 v5, v1, v0 offset:20
	ds_bpermute_b32 v6, v1, v0 offset:24
	ds_bpermute_b32 v7, v1, v0 offset:12
	s_waitcnt lgkmcnt(4)
	v_lshl_or_b32 v2, v3, 8, v2
	ds_bpermute_b32 v3, v1, v0 offset:8
	ds_bpermute_b32 v0, v1, v0 offset:28
	s_waitcnt lgkmcnt(4)
	v_lshl_or_b32 v4, v5, 8, v4
	s_waitcnt lgkmcnt(2)
	v_lshlrev_b32_e32 v5, 24, v7
	v_cmp_eq_u32_e32 vcc, 0, v76
	s_waitcnt lgkmcnt(1)
	v_lshlrev_b32_e32 v1, 16, v3
	v_lshlrev_b32_e32 v3, 16, v6
	s_waitcnt lgkmcnt(0)
	v_lshlrev_b32_e32 v0, 24, v0
	v_or3_b32 v1, v2, v1, v5
	v_or3_b32 v0, v4, v3, v0
	ds_bpermute_b32 v2, v150, v1
	ds_bpermute_b32 v3, v150, v0
	v_lshl_or_b32 v6, v75, 5, v155
	ds_bpermute_b32 v159, v6, v1
	ds_bpermute_b32 v165, v6, v0
	s_waitcnt lgkmcnt(3)
	v_or_b32_e32 v2, v2, v1
	s_waitcnt lgkmcnt(2)
	v_or_b32_e32 v3, v3, v0
	ds_bpermute_b32 v4, v151, v2
	ds_bpermute_b32 v5, v151, v3
	s_waitcnt lgkmcnt(1)
	v_or_b32_e32 v2, v4, v2
	s_waitcnt lgkmcnt(0)
	v_or_b32_e32 v3, v5, v3
	ds_bpermute_b32 v4, v148, v2
	ds_bpermute_b32 v5, v148, v3
	s_waitcnt lgkmcnt(1)
	v_or_b32_e32 v1, v4, v2
	s_waitcnt lgkmcnt(0)
	v_or_b32_e32 v0, v5, v3
	v_readfirstlane_b32 s0, v1
	v_readfirstlane_b32 s1, v0
	s_and_saveexec_b64 s[6:7], vcc
	s_add_i32 s8, s16, 0
	s_add_i32 s8, s8, 0x22200
	v_mov_b32_e32 v0, s8
	v_mov_b64_e32 v[2:3], s[0:1]
	ds_write_b64 v0, v[2:3]
	s_or_b64 exec, exec, s[6:7]
	v_mov_b32_e32 v0, s44
	s_waitcnt lgkmcnt(0)
	s_barrier
	ds_read_b128 v[0:3], v0
	v_readlane_b32 s6, v253, 24
	s_sub_i32 s8, 64, s33
	s_lshl_b64 s[8:9], -1, s8
	s_not_b64 s[8:9], s[8:9]
	s_waitcnt lgkmcnt(0)
	v_or_b32_e32 v4, v2, v0
	v_mov_b32_e32 v0, s6
	v_or_b32_e32 v5, v3, v1
	ds_read_b128 v[0:3], v0
	v_readlane_b32 s6, v253, 25
	s_cmp_lg_u32 s33, 0
	s_cselect_b32 s9, s9, -1
	s_cselect_b32 s8, s8, -1
	s_waitcnt lgkmcnt(0)
	v_or_b32_e32 v0, v4, v0
	v_or_b32_e32 v1, v5, v1
	v_or_b32_e32 v4, v0, v2
	v_mov_b32_e32 v0, s6
	v_or_b32_e32 v5, v1, v3
	ds_read_b128 v[0:3], v0
	v_readlane_b32 s6, v253, 26
	v_lshlrev_b32_e32 v138, 4, v32
	s_waitcnt lgkmcnt(0)
	v_or_b32_e32 v0, v4, v0
	v_or_b32_e32 v1, v5, v1
	v_or_b32_e32 v4, v0, v2
	v_mov_b32_e32 v0, s6
	v_or_b32_e32 v5, v1, v3
	ds_read_b128 v[0:3], v0
	s_waitcnt lgkmcnt(0)
	v_or_b32_e32 v0, v4, v0
	v_or_b32_e32 v1, v5, v1
	v_or_b32_e32 v0, v0, v2
	v_or_b32_e32 v1, v1, v3
	v_readfirstlane_b32 s6, v0
	v_readfirstlane_b32 s7, v1
	v_ashrrev_i32_e32 v0, 3, v74
	s_and_b64 s[78:79], s[6:7], s[8:9]
	s_waitcnt vmcnt(8)
	v_mad_u64_u32 v[142:143], s[6:7], v0, s3, v[138:139]
	s_cmp_lg_u64 s[78:79], 0
	s_cselect_b64 s[6:7], -1, 0
	v_lshl_or_b32 v160, v0, 13, v138
	s_ff1_i32_b64 s80, s[78:79]
	v_mov_b32_e32 v143, v161
	s_and_b64 vcc, exec, s[6:7]
	v_mul_lo_u32 v152, v0, s22
	v_mul_lo_u32 v153, v0, s27
	s_cbranch_vccz .LBB0_255
	s_lshl_b64 s[8:9], s[80:81], 7
	s_mul_i32 s10, s80, 0x88c00
	s_add_u32 s10, s40, s10
	s_addc_u32 s11, s41, 0
	global_load_dwordx4 v[96:99], v142, s[10:11]
	s_add_u32 s8, s38, s8
	s_addc_u32 s9, s39, s9
	global_load_dwordx4 v[100:103], v160, s[8:9]
	v_mul_lo_u32 v1, v0, s22
	v_add3_u32 v1, s26, v1, v138
	s_waitcnt vmcnt(1)
	ds_write_b128 v1, v[96:99]
	v_mul_lo_u32 v1, v0, s27
	v_add3_u32 v1, s28, v1, v138
	s_waitcnt vmcnt(0)
	ds_write2_b64 v1, v[100:101], v[102:103] offset1:1
	s_cbranch_execnz .LBB0_240
